# attention bias table built once into a persistent LDS region
# baseline (speedup 1.0000x reference)
; #define LAS __attribute__((address_space(3)))
; #define INP(k) inptr(k)
; __device__ __forceinline__ void attn_phase(const Args& a, LAS unsigned char* lds, int layer, int G, int vb) {
;     int tid_ = threadIdx.x; asm volatile("" : "+v"(tid_));
;     const int tid = tid_, lane = tid & 63, h = __builtin_amdgcn_readfirstlane(tid >> 6), kvh = h >> 2;
;     LAS float* biasT = (LAS float*)lds;
;     LAS float* red = (LAS float*)(lds + 10240);
;     const float* tab = INP(1);
;     for (int e = tid; e < 8 * 320; e += NTHREADS) {
;         const int hh = e / 320, ri = e % 320 - 32; float v = -1e30f;
;         if (ri >= 0 && ri <= 256) { const int rel = ri - 128, n = rel < 0 ? -rel : rel; int bk = (rel > 0) ? 16 : 0;
;             if (n < 8) bk += n; else { int lg = 2 + (31 - __builtin_clz((unsigned)(n * n))); bk += (lg < 15 ? lg : 15); }
;             v = tab[bk * 8 + hh] * LOG2E; }
;         biasT[e] = v;
;     }
;     __syncthreads();
.LBB0_662:
	s_or_b64 exec, exec, s[4:5]
	v_mov_b32_e32 v0, v209
	s_waitcnt lgkmcnt(0)
	s_barrier
	s_mov_b32 s6, 8
	v_readfirstlane_b32 s19, v0
	s_cmp_lg_u32 s17, 0
	s_cbranch_scc1 .Lbias_skip
	v_cmp_gt_i32_e32 vcc, s44, v0
	s_and_saveexec_b64 s[4:5], vcc
	s_cbranch_execz .LBB0_671
	s_ashr_i32 s7, s6, 31
	s_add_u32 s6, s0, s6
	s_addc_u32 s7, s1, s7
	s_load_dwordx2 s[6:7], s[6:7], 0x0
	v_sub_u32_e32 v2, 0xa0, v0
	v_lshl_add_u32 v3, v0, 2, 0
	v_add_u32_e32 v3, 0x20810, v3
	s_mov_b64 s[8:9], 0
	v_mov_b32_e32 v4, v0
	s_branch .LBB0_666

; #define INP(k) inptr(k)
; #define WSPTR() kptr(224)
; __device__ __forceinline__ void attn_phase(const Args& a, LAS unsigned char* lds, int layer, int G, int vb) {
;     ...
;     const bf16* proj = (const bf16*)(WSPTR() + WS_PROJ); const bf16* vT = (const bf16*)(WSPTR() + WS_VT); bf16* an = (bf16*)(WSPTR() + WS_MIX); const float* ssq2p = (const float*)(WSPTR() + WS_SSQ2);
;     const float sinkv = INP(8)[layer * 8 + h] * LOG2E;
;     const int ql = lane & 31, hi = lane >> 5;
;     int par = 0;
;     for (int ui = vb; ui < 1024; ui += G, par ^= 1) {
;         const int b = ui & 7, q0 = (ui >> 3) * 32, rowq = b * SEQ + q0;
;         const bf16* qp = proj + (size_t)(rowq + ql) * DIN + h * 64 + 8 * hi;
;         bf16x8 qf[4];
; #pragma unroll
;         for (int kk = 0; kk < 4; ++kk) qf[kk] = *(const bf16x8*)(qp + 16 * kk);
;         float m = sinkv, lsum = 1.0f;
;         f32x16 o0, o1;
; #pragma unroll
;         for (int r = 0; r < 16; ++r) { o0[r] = 0.f; o1[r] = 0.f; }
;         const bf16* vbase = vT + ((size_t)(b * 2 + kvh) * 64 + ql) * SEQ + 4 * hi;
;         const bf16* kbase = proj + (size_t)(b * SEQ + ql) * DIN + 512 + kvh * 64 + 8 * hi;
;         const int rb = ui >> 3, kt_lo = (4 - rb) > 0 ? (4 - rb) : 0, kt_hi = (132 - rb) < 9 ? (132 - rb) : 9;
;         bf16x8 kf[4]; s16x4 vf[2][2][2];
;     ...
;         bf16x8 kg[4]; s16x4 vg[2][2][2];
.Lbias_skip:
	v_readlane_b32 s22, v254, 5
	v_readlane_b32 s23, v254, 6
	s_movk_i32 s8, 0xe0
	s_waitcnt lgkmcnt(0)
	s_movk_i32 s7, 0xe0
	s_movk_i32 s6, 0xe0
	s_movk_i32 s5, 0xe0
	s_mov_b32 s4, 64
	s_andn2_b64 vcc, exec, s[22:23]
	s_barrier
	s_cmpk_gt_i32 s33, 0x3ff
	s_cbranch_scc1 .LBB0_686
	s_load_dwordx2 s[4:5], s[0:1], 0xe0
	s_load_dwordx2 s[76:77], s[0:1], 0x40
	v_readfirstlane_b32 s18, v209
	v_and_b32_e32 v160, 63, v209
	s_lshr_b32 s18, s18, 6
	v_and_b32_e32 v2, 31, v160
	v_lshrrev_b32_e32 v3, 5, v160
	s_lshr_b32 s19, s18, 2
	s_and_b32 s22, s18, 3
	s_lshl_b32 s78, s17, 3
	s_add_i32 s78, s78, s18
	s_lshl_b32 s78, s78, 2
	s_waitcnt lgkmcnt(0)
	s_load_dword s45, s[76:77], s78
	v_lshrrev_b32_e32 v161, 3, v160
	v_and_b32_e32 v178, 7, v160
	v_xor_b32_e32 v178, v178, v161
	v_mul_u32_u24_e32 v5, 0xa00, v161
	v_lshl_add_u32 v5, v178, 4, v5
	v_lshrrev_b32_e32 v161, 2, v160
	v_lshlrev_b32_e32 v6, 13, v161
	v_bfe_u32 v178, v160, 4, 2
	v_and_b32_e32 v179, 3, v160
	v_xor_b32_e32 v178, v178, v179
	v_lshl_add_u32 v6, v178, 4, v6
	s_mul_i32 s78, s18, 0x500
	s_add_i32 s78, s78, 0x20890
	v_lshlrev_b32_e32 v161, 4, v3
	v_lshlrev_b32_e32 v178, 2, v2
	v_sub_u32_e32 v7, v161, v178
	v_add_u32_e32 v7, s78, v7
	v_and_b32_e32 v161, 7, v2
	v_lshlrev_b32_e32 v178, 7, v2
	v_or_b32_e32 v179, 0, v3
	v_xor_b32_e32 v179, v179, v161
	v_lshl_add_u32 v142, v179, 4, v178
	v_or_b32_e32 v179, 2, v3
	v_xor_b32_e32 v179, v179, v161
	v_lshl_add_u32 v143, v179, 4, v178
	v_or_b32_e32 v179, 4, v3
	v_xor_b32_e32 v179, v179, v161
	v_lshl_add_u32 v144, v179, 4, v178
	v_or_b32_e32 v179, 6, v3
	v_xor_b32_e32 v179, v179, v161
	v_lshl_add_u32 v145, v179, 4, v178
	v_bfe_u32 v161, v2, 2, 2
	v_lshlrev_b32_e32 v178, 6, v2
	v_lshl_add_u32 v178, v3, 3, v178
	v_add_u32_e32 v178, 0x1000, v178
	v_xor_b32_e32 v179, 0, v161
	v_lshl_add_u32 v146, v179, 4, v178
	v_xor_b32_e32 v179, 1, v161
	v_lshl_add_u32 v147, v179, 4, v178
	v_xor_b32_e32 v179, 2, v161
	v_lshl_add_u32 v148, v179, 4, v178
	v_xor_b32_e32 v179, 3, v161
	v_lshl_add_u32 v149, v179, 4, v178
	v_mul_u32_u24_e32 v180, 0xa00, v2
	v_lshl_add_u32 v180, v3, 4, v180
	v_lshlrev_b32_e32 v181, 19, v3
	v_lshl_add_u32 v181, v2, 4, v181
	v_lshlrev_b32_e32 v182, 11, v2
	v_lshl_add_u32 v182, v3, 3, v182
	s_lshl_b32 s78, s18, 7
	s_add_i32 s78, s78, 10240
	v_lshl_add_u32 v196, v2, 2, s78
	v_lshlrev_b32_e32 v197, 2, v2
	v_add_u32_e32 v197, 10240, v197
	s_waitcnt lgkmcnt(0)
	v_mov_b32_e32 v183, 0x3fb8aa3b
	v_mul_f32_e32 v183, s45, v183
	s_mov_b32 s23, s33
	s_mov_b32 s37, 0
	s_lshl_b32 s94, s19, 13
	s_lshl_b32 s95, s22, 10
	s_add_i32 s93, s94, 16384
	s_add_i32 s92, s93, s95
